# merge phase rewritten by hand: all loads of a token issued up front, next token prefetched (2 register buffers), DPP reductions
# speedup vs baseline: 1.1018x; 1.1018x over previous
.LBB0_1221:
	s_or_b64 exec, exec, s[10:11]
	s_cmpk_lt_i32 s2, 0x800
	s_cselect_b64 s[10:11], -1, 0
	s_and_b64 vcc, exec, s[10:11]
	s_waitcnt lgkmcnt(0)
	s_barrier
	s_cbranch_vccz .LBB0_1224
	v_lshrrev_b32_e32 v0, 6, v141
	v_and_b32_e32 v1, 63, v141
	s_mov_b32 s44, 0xbfb8aa3b
	v_readfirstlane_b32 s13, v0
	s_mov_b32 s45, 0xbfb8aa3b
	v_lshlrev_b32_e32 v4, 4, v1
	v_lshrrev_b32_e32 v2, 3, v1
	v_lshlrev_b32_e32 v0, 5, v1
	v_lshlrev_b32_e32 v5, 2, v2
	v_mul_u32_u24_e32 v6, 0x318000, v2
	global_load_dwordx4 v[8:11], v0, s[46:47]
	global_load_dwordx4 v[12:15], v0, s[46:47] offset:16
	global_load_dwordx4 v[16:19], v0, s[48:49]
	global_load_dwordx4 v[20:23], v0, s[48:49] offset:16
	v_and_b32_e32 v7, 7, v1
	v_lshrrev_b32_e32 v2, 1, v7
	v_and_b32_e32 v7, 1, v7
	v_lshlrev_b32_e32 v2, 9, v2
	v_lshlrev_b32_e32 v7, 6, v7
	v_add3_u32 v7, v6, v2, v7
	v_mov_b32_e32 v100, 0x3a27c5ac
	s_mov_b32 s12, s2
	s_lshl_b32 s16, s12, 3
	s_add_i32 s16, s16, s13
	s_mul_i32 s17, s16, 0x2100
	s_add_u32 s24, s78, s17
	s_addc_u32 s25, s79, 0
	s_add_u32 s26, s24, 0x1900
	s_addc_u32 s27, s25, 0
	s_lshl_b32 s17, s16, 10
	s_add_u32 s28, s80, s17
	s_addc_u32 s29, s81, 0
	s_lshr_b32 s17, s16, 12
	s_lshl_b32 s17, s17, 11
	s_bfe_u32 s19, s16, 0x80004
	s_add_i32 s17, s17, s19
	s_mul_i32 s17, s17, 0x3180
	s_add_u32 s68, s86, s17
	s_addc_u32 s69, s87, 0
	s_and_b32 s19, s16, 15
	s_lshl_b32 s17, s19, 2
	s_addk_i32 s17, 0x3100
	s_add_u32 s30, s68, s17
	s_addc_u32 s31, s69, 0
	s_lshr_b32 s17, s19, 2
	s_lshl_b32 s17, s17, 7
	s_and_b32 s19, s19, 3
	s_lshl_b32 s19, s19, 1
	s_add_i32 s17, s17, s19
	s_addk_i32 s17, 0x2800
	s_add_u32 s32, s68, s17
	s_addc_u32 s33, s69, 0
	global_load_dword v24, v5, s[24:25] offset:3072
	global_load_dword v25, v5, s[24:25] offset:3104
	global_load_dword v26, v5, s[24:25] offset:3136
	global_load_dwordx4 v[28:31], v4, s[24:25] nt
	global_load_dwordx4 v[32:35], v4, s[24:25] offset:1024 nt
	global_load_dwordx4 v[36:39], v4, s[24:25] offset:2048 nt
	global_load_dwordx4 v[44:47], v4, s[26:27] offset:1024 nt
	global_load_dwordx4 v[48:51], v4, s[28:29] nt
	global_load_dwordx4 v[52:55], v4, s[26:27] nt
	global_load_dword v27, v6, s[30:31]
	global_load_ushort v56, v7, s[32:33] offset:0
	global_load_ushort v57, v7, s[32:33] offset:8
	global_load_ushort v58, v7, s[32:33] offset:16
	global_load_ushort v59, v7, s[32:33] offset:24
	global_load_ushort v60, v7, s[32:33] offset:32
	global_load_ushort v61, v7, s[32:33] offset:40
	global_load_ushort v62, v7, s[32:33] offset:48
	global_load_ushort v63, v7, s[32:33] offset:56
	s_mov_b32 s50, 1
.Lmg_loop:
	s_lshl_b32 s16, s12, 3
	s_add_i32 s16, s16, s13
	s_addk_i32 s16, 0x4000
	s_mul_i32 s17, s16, 0x2100
	s_add_u32 s58, s78, s17
	s_addc_u32 s59, s79, 0
	s_add_u32 s60, s58, 0x1900
	s_addc_u32 s61, s59, 0
	s_lshl_b32 s17, s16, 10
	s_add_u32 s62, s80, s17
	s_addc_u32 s63, s81, 0
	s_lshr_b32 s17, s16, 12
	s_lshl_b32 s17, s17, 11
	s_bfe_u32 s19, s16, 0x80004
	s_add_i32 s17, s17, s19
	s_mul_i32 s17, s17, 0x3180
	s_add_u32 s68, s86, s17
	s_addc_u32 s69, s87, 0
	s_and_b32 s19, s16, 15
	s_lshl_b32 s17, s19, 2
	s_addk_i32 s17, 0x3100
	s_add_u32 s64, s68, s17
	s_addc_u32 s65, s69, 0
	s_lshr_b32 s17, s19, 2
	s_lshl_b32 s17, s17, 7
	s_and_b32 s19, s19, 3
	s_lshl_b32 s19, s19, 1
	s_add_i32 s17, s17, s19
	s_addk_i32 s17, 0x2800
	s_add_u32 s66, s68, s17
	s_addc_u32 s67, s69, 0
	global_load_dword v64, v5, s[58:59] offset:3072
	global_load_dword v65, v5, s[58:59] offset:3104
	global_load_dword v66, v5, s[58:59] offset:3136
	global_load_dwordx4 v[68:71], v4, s[58:59] nt
	global_load_dwordx4 v[72:75], v4, s[58:59] offset:1024 nt
	global_load_dwordx4 v[76:79], v4, s[58:59] offset:2048 nt
	global_load_dwordx4 v[80:83], v4, s[60:61] offset:1024 nt
	global_load_dwordx4 v[84:87], v4, s[62:63] nt
	global_load_dwordx4 v[88:91], v4, s[60:61] nt
	global_load_dword v67, v6, s[64:65]
	global_load_ushort v92, v7, s[66:67] offset:0
	global_load_ushort v93, v7, s[66:67] offset:8
	global_load_ushort v94, v7, s[66:67] offset:16
	global_load_ushort v95, v7, s[66:67] offset:24
	global_load_ushort v96, v7, s[66:67] offset:32
	global_load_ushort v97, v7, s[66:67] offset:40
	global_load_ushort v98, v7, s[66:67] offset:48
	global_load_ushort v99, v7, s[66:67] offset:56
	s_cmp_eq_u32 s50, 0
	s_cbranch_scc1 .Lmg_w20
	s_waitcnt vmcnt(18)
	s_branch .Lmg_wdone
.Lmg_w20:
	s_waitcnt vmcnt(20)
.Lmg_wdone:
	v_max3_f32 v127, v24, v25, v26
	v_sub_f32_e32 v102, v24, v127
	v_sub_f32_e32 v104, v25, v127
	v_sub_f32_e32 v106, v26, v127
	v_mul_f32_e32 v102, 0x3fb8aa3b, v102
	v_mul_f32_e32 v104, 0x3fb8aa3b, v104
	v_mul_f32_e32 v106, 0x3fb8aa3b, v106
	v_exp_f32_e32 v102, v102
	v_exp_f32_e32 v104, v104
	v_exp_f32_e32 v106, v106
	s_nop 0
	v_add_f32_e32 v127, v102, v104
	v_add_f32_e32 v127, v106, v127
	v_div_scale_f32 v122, s[36:37], v127, v127, 1.0
	v_rcp_f32_e32 v123, v122
	v_div_scale_f32 v124, vcc, 1.0, v127, 1.0
	v_fma_f32 v126, -v122, v123, 1.0
	v_fmac_f32_e32 v123, v126, v123
	v_mul_f32_e32 v125, v124, v123
	v_fma_f32 v126, -v122, v125, v124
	v_fmac_f32_e32 v125, v126, v123
	v_fma_f32 v122, -v122, v125, v124
	v_div_fmas_f32 v122, v122, v123, v125
	v_div_fixup_f32 v103, v122, v127, 1.0
	v_mul_f32_e32 v102, v102, v103
	v_mul_f32_e32 v104, v104, v103
	v_mul_f32_e32 v106, v106, v103
	v_lshlrev_b32_e32 v108, 16, v28
	v_and_b32_e32 v109, 0xffff0000, v28
	v_lshlrev_b32_e32 v110, 16, v32
	v_and_b32_e32 v111, 0xffff0000, v32
	v_lshlrev_b32_e32 v112, 16, v36
	v_and_b32_e32 v113, 0xffff0000, v36
	v_lshlrev_b32_e32 v114, 16, v44
	v_and_b32_e32 v115, 0xffff0000, v44
	v_pk_mul_f32 v[116:117], v[108:109], v[102:103] op_sel_hi:[1,0]
	v_pk_fma_f32 v[116:117], v[110:111], v[104:105], v[116:117] op_sel_hi:[1,0,1]
	v_pk_fma_f32 v[116:117], v[112:113], v[106:107], v[116:117] op_sel_hi:[1,0,1]
	v_pk_mul_f32 v[118:119], v[114:115], s[44:45]
	v_exp_f32_e32 v118, v118
	v_exp_f32_e32 v119, v119
	s_nop 0
	v_pk_add_f32 v[118:119], v[118:119], 1.0 op_sel_hi:[1,0]
	v_div_scale_f32 v122, s[36:37], v118, v118, v114
	v_rcp_f32_e32 v123, v122
	v_div_scale_f32 v124, vcc, v114, v118, v114
	v_fma_f32 v126, -v122, v123, 1.0
	v_fmac_f32_e32 v123, v126, v123
	v_mul_f32_e32 v125, v124, v123
	v_fma_f32 v126, -v122, v125, v124
	v_fmac_f32_e32 v125, v126, v123
	v_fma_f32 v122, -v122, v125, v124
	v_div_fmas_f32 v122, v122, v123, v125
	v_div_fixup_f32 v120, v122, v118, v114
	v_div_scale_f32 v122, s[36:37], v119, v119, v115
	v_rcp_f32_e32 v123, v122
	v_div_scale_f32 v124, vcc, v115, v119, v115
	v_fma_f32 v126, -v122, v123, 1.0
	v_fmac_f32_e32 v123, v126, v123
	v_mul_f32_e32 v125, v124, v123
	v_fma_f32 v126, -v122, v125, v124
	v_fmac_f32_e32 v125, v126, v123
	v_fma_f32 v122, -v122, v125, v124
	v_div_fmas_f32 v122, v122, v123, v125
	v_div_fixup_f32 v121, v122, v119, v115
	v_pk_mul_f32 v[116:117], v[120:121], v[116:117]
	v_cvt_pk_bf16_f32 v128, v116, v117
	v_lshlrev_b32_e32 v108, 16, v29
	v_and_b32_e32 v109, 0xffff0000, v29
	v_lshlrev_b32_e32 v110, 16, v33
	v_and_b32_e32 v111, 0xffff0000, v33
	v_lshlrev_b32_e32 v112, 16, v37
	v_and_b32_e32 v113, 0xffff0000, v37
	v_lshlrev_b32_e32 v114, 16, v45
	v_and_b32_e32 v115, 0xffff0000, v45
	v_pk_mul_f32 v[116:117], v[108:109], v[102:103] op_sel_hi:[1,0]
	v_pk_fma_f32 v[116:117], v[110:111], v[104:105], v[116:117] op_sel_hi:[1,0,1]
	v_pk_fma_f32 v[116:117], v[112:113], v[106:107], v[116:117] op_sel_hi:[1,0,1]
	v_pk_mul_f32 v[118:119], v[114:115], s[44:45]
	v_exp_f32_e32 v118, v118
	v_exp_f32_e32 v119, v119
	s_nop 0
	v_pk_add_f32 v[118:119], v[118:119], 1.0 op_sel_hi:[1,0]
	v_div_scale_f32 v122, s[36:37], v118, v118, v114
	v_rcp_f32_e32 v123, v122
	v_div_scale_f32 v124, vcc, v114, v118, v114
	v_fma_f32 v126, -v122, v123, 1.0
	v_fmac_f32_e32 v123, v126, v123
	v_mul_f32_e32 v125, v124, v123
	v_fma_f32 v126, -v122, v125, v124
	v_fmac_f32_e32 v125, v126, v123
	v_fma_f32 v122, -v122, v125, v124
	v_div_fmas_f32 v122, v122, v123, v125
	v_div_fixup_f32 v120, v122, v118, v114
	v_div_scale_f32 v122, s[36:37], v119, v119, v115
	v_rcp_f32_e32 v123, v122
	v_div_scale_f32 v124, vcc, v115, v119, v115
	v_fma_f32 v126, -v122, v123, 1.0
	v_fmac_f32_e32 v123, v126, v123
	v_mul_f32_e32 v125, v124, v123
	v_fma_f32 v126, -v122, v125, v124
	v_fmac_f32_e32 v125, v126, v123
	v_fma_f32 v122, -v122, v125, v124
	v_div_fmas_f32 v122, v122, v123, v125
	v_div_fixup_f32 v121, v122, v119, v115
	v_pk_mul_f32 v[116:117], v[120:121], v[116:117]
	v_cvt_pk_bf16_f32 v129, v116, v117
	v_lshlrev_b32_e32 v108, 16, v30
	v_and_b32_e32 v109, 0xffff0000, v30
	v_lshlrev_b32_e32 v110, 16, v34
	v_and_b32_e32 v111, 0xffff0000, v34
	v_lshlrev_b32_e32 v112, 16, v38
	v_and_b32_e32 v113, 0xffff0000, v38
	v_lshlrev_b32_e32 v114, 16, v46
	v_and_b32_e32 v115, 0xffff0000, v46
	v_pk_mul_f32 v[116:117], v[108:109], v[102:103] op_sel_hi:[1,0]
	v_pk_fma_f32 v[116:117], v[110:111], v[104:105], v[116:117] op_sel_hi:[1,0,1]
	v_pk_fma_f32 v[116:117], v[112:113], v[106:107], v[116:117] op_sel_hi:[1,0,1]
	v_pk_mul_f32 v[118:119], v[114:115], s[44:45]
	v_exp_f32_e32 v118, v118
	v_exp_f32_e32 v119, v119
	s_nop 0
	v_pk_add_f32 v[118:119], v[118:119], 1.0 op_sel_hi:[1,0]
	v_div_scale_f32 v122, s[36:37], v118, v118, v114
	v_rcp_f32_e32 v123, v122
	v_div_scale_f32 v124, vcc, v114, v118, v114
	v_fma_f32 v126, -v122, v123, 1.0
	v_fmac_f32_e32 v123, v126, v123
	v_mul_f32_e32 v125, v124, v123
	v_fma_f32 v126, -v122, v125, v124
	v_fmac_f32_e32 v125, v126, v123
	v_fma_f32 v122, -v122, v125, v124
	v_div_fmas_f32 v122, v122, v123, v125
	v_div_fixup_f32 v120, v122, v118, v114
	v_div_scale_f32 v122, s[36:37], v119, v119, v115
	v_rcp_f32_e32 v123, v122
	v_div_scale_f32 v124, vcc, v115, v119, v115
	v_fma_f32 v126, -v122, v123, 1.0
	v_fmac_f32_e32 v123, v126, v123
	v_mul_f32_e32 v125, v124, v123
	v_fma_f32 v126, -v122, v125, v124
	v_fmac_f32_e32 v125, v126, v123
	v_fma_f32 v122, -v122, v125, v124
	v_div_fmas_f32 v122, v122, v123, v125
	v_div_fixup_f32 v121, v122, v119, v115
	v_pk_mul_f32 v[116:117], v[120:121], v[116:117]
	v_cvt_pk_bf16_f32 v130, v116, v117
	v_lshlrev_b32_e32 v108, 16, v31
	v_and_b32_e32 v109, 0xffff0000, v31
	v_lshlrev_b32_e32 v110, 16, v35
	v_and_b32_e32 v111, 0xffff0000, v35
	v_lshlrev_b32_e32 v112, 16, v39
	v_and_b32_e32 v113, 0xffff0000, v39
	v_lshlrev_b32_e32 v114, 16, v47
	v_and_b32_e32 v115, 0xffff0000, v47
	v_pk_mul_f32 v[116:117], v[108:109], v[102:103] op_sel_hi:[1,0]
	v_pk_fma_f32 v[116:117], v[110:111], v[104:105], v[116:117] op_sel_hi:[1,0,1]
	v_pk_fma_f32 v[116:117], v[112:113], v[106:107], v[116:117] op_sel_hi:[1,0,1]
	v_pk_mul_f32 v[118:119], v[114:115], s[44:45]
	v_exp_f32_e32 v118, v118
	v_exp_f32_e32 v119, v119
	s_nop 0
	v_pk_add_f32 v[118:119], v[118:119], 1.0 op_sel_hi:[1,0]
	v_div_scale_f32 v122, s[36:37], v118, v118, v114
	v_rcp_f32_e32 v123, v122
	v_div_scale_f32 v124, vcc, v114, v118, v114
	v_fma_f32 v126, -v122, v123, 1.0
	v_fmac_f32_e32 v123, v126, v123
	v_mul_f32_e32 v125, v124, v123
	v_fma_f32 v126, -v122, v125, v124
	v_fmac_f32_e32 v125, v126, v123
	v_fma_f32 v122, -v122, v125, v124
	v_div_fmas_f32 v122, v122, v123, v125
	v_div_fixup_f32 v120, v122, v118, v114
	v_div_scale_f32 v122, s[36:37], v119, v119, v115
	v_rcp_f32_e32 v123, v122
	v_div_scale_f32 v124, vcc, v115, v119, v115
	v_fma_f32 v126, -v122, v123, 1.0
	v_fmac_f32_e32 v123, v126, v123
	v_mul_f32_e32 v125, v124, v123
	v_fma_f32 v126, -v122, v125, v124
	v_fmac_f32_e32 v125, v126, v123
	v_fma_f32 v122, -v122, v125, v124
	v_div_fmas_f32 v122, v122, v123, v125
	v_div_fixup_f32 v121, v122, v119, v115
	v_pk_mul_f32 v[116:117], v[120:121], v[116:117]
	v_cvt_pk_bf16_f32 v131, v116, v117
	global_store_dwordx4 v4, v[128:131], s[26:27] offset:1024
	v_lshlrev_b32_e32 v28, 16, v48
	v_and_b32_e32 v29, 0xffff0000, v48
	v_lshlrev_b32_e32 v30, 16, v49
	v_and_b32_e32 v31, 0xffff0000, v49
	v_lshlrev_b32_e32 v32, 16, v50
	v_and_b32_e32 v33, 0xffff0000, v50
	v_lshlrev_b32_e32 v34, 16, v51
	v_and_b32_e32 v35, 0xffff0000, v51
	v_lshlrev_b32_e32 v36, 16, v52
	v_and_b32_e32 v37, 0xffff0000, v52
	v_lshlrev_b32_e32 v38, 16, v53
	v_and_b32_e32 v39, 0xffff0000, v53
	v_lshlrev_b32_e32 v44, 16, v54
	v_and_b32_e32 v45, 0xffff0000, v54
	v_lshlrev_b32_e32 v46, 16, v55
	v_and_b32_e32 v47, 0xffff0000, v55
	v_lshlrev_b32_e32 v56, 16, v56
	v_lshlrev_b32_e32 v57, 16, v57
	v_lshlrev_b32_e32 v58, 16, v58
	v_lshlrev_b32_e32 v59, 16, v59
	v_lshlrev_b32_e32 v60, 16, v60
	v_lshlrev_b32_e32 v61, 16, v61
	v_lshlrev_b32_e32 v62, 16, v62
	v_lshlrev_b32_e32 v63, 16, v63
	v_add_f32_e32 v108, v28, v29
	v_add_f32_e32 v108, v108, v30
	v_add_f32_e32 v108, v108, v31
	v_add_f32_e32 v108, v108, v32
	v_add_f32_e32 v108, v108, v33
	v_add_f32_e32 v108, v108, v34
	v_add_f32_e32 v108, v108, v35
	s_nop 1
	v_add_f32_dpp v109, v108, v108 quad_perm:[1,0,3,2] row_mask:0xf bank_mask:0xf
	s_nop 1
	v_add_f32_dpp v108, v109, v109 quad_perm:[2,3,0,1] row_mask:0xf bank_mask:0xf
	s_nop 1
	v_add_f32_dpp v109, v108, v108 row_half_mirror row_mask:0xf bank_mask:0xf
	v_mov_b32_e32 v108, v109
	v_mul_f32_e32 v108, 0x3c800000, v108
	v_pk_add_f32 v[28:29], v[28:29], v[108:109] op_sel_hi:[1,0] neg_lo:[0,1] neg_hi:[0,1]
	v_pk_add_f32 v[30:31], v[30:31], v[108:109] op_sel_hi:[1,0] neg_lo:[0,1] neg_hi:[0,1]
	v_pk_add_f32 v[32:33], v[32:33], v[108:109] op_sel_hi:[1,0] neg_lo:[0,1] neg_hi:[0,1]
	v_pk_add_f32 v[34:35], v[34:35], v[108:109] op_sel_hi:[1,0] neg_lo:[0,1] neg_hi:[0,1]
	v_pk_mul_f32 v[110:111], v[28:29], v[28:29]
	v_pk_mul_f32 v[112:113], v[30:31], v[30:31]
	v_pk_mul_f32 v[114:115], v[32:33], v[32:33]
	v_pk_mul_f32 v[116:117], v[34:35], v[34:35]
	v_add_f32_e32 v118, v110, v111
	v_add_f32_e32 v118, v112, v118
	v_add_f32_e32 v118, v113, v118
	v_add_f32_e32 v118, v114, v118
	v_add_f32_e32 v118, v115, v118
	v_add_f32_e32 v118, v116, v118
	v_add_f32_e32 v118, v117, v118
	s_nop 1
	v_add_f32_dpp v119, v118, v118 quad_perm:[1,0,3,2] row_mask:0xf bank_mask:0xf
	s_nop 1
	v_add_f32_dpp v118, v119, v119 quad_perm:[2,3,0,1] row_mask:0xf bank_mask:0xf
	s_nop 1
	v_add_f32_dpp v119, v118, v118 row_half_mirror row_mask:0xf bank_mask:0xf
	v_mov_b32_e32 v118, v119
	v_fmamk_f32 v118, v118, 0x3c800000, v100
	v_rsq_f32_e32 v118, v118
	v_mov_b32_e32 v120, v27
	v_pk_mul_f32 v[28:29], v[28:29], v[118:119] op_sel_hi:[1,0]
	v_pk_mul_f32 v[30:31], v[30:31], v[118:119] op_sel_hi:[1,0]
	v_pk_mul_f32 v[32:33], v[32:33], v[118:119] op_sel_hi:[1,0]
	v_pk_mul_f32 v[34:35], v[34:35], v[118:119] op_sel_hi:[1,0]
	v_pk_fma_f32 v[28:29], v[8:9], v[28:29], v[16:17]
	v_pk_fma_f32 v[30:31], v[10:11], v[30:31], v[18:19]
	v_pk_fma_f32 v[32:33], v[12:13], v[32:33], v[20:21]
	v_pk_fma_f32 v[34:35], v[14:15], v[34:35], v[22:23]
	v_pk_fma_f32 v[28:29], v[120:121], v[56:57], v[28:29] op_sel_hi:[0,1,1]
	v_pk_fma_f32 v[30:31], v[120:121], v[58:59], v[30:31] op_sel_hi:[0,1,1]
	v_pk_fma_f32 v[32:33], v[120:121], v[60:61], v[32:33] op_sel_hi:[0,1,1]
	v_pk_fma_f32 v[34:35], v[120:121], v[62:63], v[34:35] op_sel_hi:[0,1,1]
	v_pk_mul_f32 v[118:119], v[36:37], s[44:45]
	v_exp_f32_e32 v118, v118
	v_exp_f32_e32 v119, v119
	s_nop 0
	v_pk_add_f32 v[118:119], v[118:119], 1.0 op_sel_hi:[1,0]
	v_div_scale_f32 v122, s[36:37], v118, v118, v36
	v_rcp_f32_e32 v123, v122
	v_div_scale_f32 v124, vcc, v36, v118, v36
	v_fma_f32 v126, -v122, v123, 1.0
	v_fmac_f32_e32 v123, v126, v123
	v_mul_f32_e32 v125, v124, v123
	v_fma_f32 v126, -v122, v125, v124
	v_fmac_f32_e32 v125, v126, v123
	v_fma_f32 v122, -v122, v125, v124
	v_div_fmas_f32 v122, v122, v123, v125
	v_div_fixup_f32 v108, v122, v118, v36
	v_div_scale_f32 v122, s[36:37], v119, v119, v37
	v_rcp_f32_e32 v123, v122
	v_div_scale_f32 v124, vcc, v37, v119, v37
	v_fma_f32 v126, -v122, v123, 1.0
	v_fmac_f32_e32 v123, v126, v123
	v_mul_f32_e32 v125, v124, v123
	v_fma_f32 v126, -v122, v125, v124
	v_fmac_f32_e32 v125, v126, v123
	v_fma_f32 v122, -v122, v125, v124
	v_div_fmas_f32 v122, v122, v123, v125
	v_div_fixup_f32 v109, v122, v119, v37
	v_pk_mul_f32 v[28:29], v[108:109], v[28:29]
	v_cvt_pk_bf16_f32 v132, v28, v29
	v_pk_mul_f32 v[118:119], v[38:39], s[44:45]
	v_exp_f32_e32 v118, v118
	v_exp_f32_e32 v119, v119
	s_nop 0
	v_pk_add_f32 v[118:119], v[118:119], 1.0 op_sel_hi:[1,0]
	v_div_scale_f32 v122, s[36:37], v118, v118, v38
	v_rcp_f32_e32 v123, v122
	v_div_scale_f32 v124, vcc, v38, v118, v38
	v_fma_f32 v126, -v122, v123, 1.0
	v_fmac_f32_e32 v123, v126, v123
	v_mul_f32_e32 v125, v124, v123
	v_fma_f32 v126, -v122, v125, v124
	v_fmac_f32_e32 v125, v126, v123
	v_fma_f32 v122, -v122, v125, v124
	v_div_fmas_f32 v122, v122, v123, v125
	v_div_fixup_f32 v108, v122, v118, v38
	v_div_scale_f32 v122, s[36:37], v119, v119, v39
	v_rcp_f32_e32 v123, v122
	v_div_scale_f32 v124, vcc, v39, v119, v39
	v_fma_f32 v126, -v122, v123, 1.0
	v_fmac_f32_e32 v123, v126, v123
	v_mul_f32_e32 v125, v124, v123
	v_fma_f32 v126, -v122, v125, v124
	v_fmac_f32_e32 v125, v126, v123
	v_fma_f32 v122, -v122, v125, v124
	v_div_fmas_f32 v122, v122, v123, v125
	v_div_fixup_f32 v109, v122, v119, v39
	v_pk_mul_f32 v[30:31], v[108:109], v[30:31]
	v_cvt_pk_bf16_f32 v133, v30, v31
	v_pk_mul_f32 v[118:119], v[44:45], s[44:45]
	v_exp_f32_e32 v118, v118
	v_exp_f32_e32 v119, v119
	s_nop 0
	v_pk_add_f32 v[118:119], v[118:119], 1.0 op_sel_hi:[1,0]
	v_div_scale_f32 v122, s[36:37], v118, v118, v44
	v_rcp_f32_e32 v123, v122
	v_div_scale_f32 v124, vcc, v44, v118, v44
	v_fma_f32 v126, -v122, v123, 1.0
	v_fmac_f32_e32 v123, v126, v123
	v_mul_f32_e32 v125, v124, v123
	v_fma_f32 v126, -v122, v125, v124
	v_fmac_f32_e32 v125, v126, v123
	v_fma_f32 v122, -v122, v125, v124
	v_div_fmas_f32 v122, v122, v123, v125
	v_div_fixup_f32 v108, v122, v118, v44
	v_div_scale_f32 v122, s[36:37], v119, v119, v45
	v_rcp_f32_e32 v123, v122
	v_div_scale_f32 v124, vcc, v45, v119, v45
	v_fma_f32 v126, -v122, v123, 1.0
	v_fmac_f32_e32 v123, v126, v123
	v_mul_f32_e32 v125, v124, v123
	v_fma_f32 v126, -v122, v125, v124
	v_fmac_f32_e32 v125, v126, v123
	v_fma_f32 v122, -v122, v125, v124
	v_div_fmas_f32 v122, v122, v123, v125
	v_div_fixup_f32 v109, v122, v119, v45
	v_pk_mul_f32 v[32:33], v[108:109], v[32:33]
	v_cvt_pk_bf16_f32 v134, v32, v33
	v_pk_mul_f32 v[118:119], v[46:47], s[44:45]
	v_exp_f32_e32 v118, v118
	v_exp_f32_e32 v119, v119
	s_nop 0
	v_pk_add_f32 v[118:119], v[118:119], 1.0 op_sel_hi:[1,0]
	v_div_scale_f32 v122, s[36:37], v118, v118, v46
	v_rcp_f32_e32 v123, v122
	v_div_scale_f32 v124, vcc, v46, v118, v46
	v_fma_f32 v126, -v122, v123, 1.0
	v_fmac_f32_e32 v123, v126, v123
	v_mul_f32_e32 v125, v124, v123
	v_fma_f32 v126, -v122, v125, v124
	v_fmac_f32_e32 v125, v126, v123
	v_fma_f32 v122, -v122, v125, v124
	v_div_fmas_f32 v122, v122, v123, v125
	v_div_fixup_f32 v108, v122, v118, v46
	v_div_scale_f32 v122, s[36:37], v119, v119, v47
	v_rcp_f32_e32 v123, v122
	v_div_scale_f32 v124, vcc, v47, v119, v47
	v_fma_f32 v126, -v122, v123, 1.0
	v_fmac_f32_e32 v123, v126, v123
	v_mul_f32_e32 v125, v124, v123
	v_fma_f32 v126, -v122, v125, v124
	v_fmac_f32_e32 v125, v126, v123
	v_fma_f32 v122, -v122, v125, v124
	v_div_fmas_f32 v122, v122, v123, v125
	v_div_fixup_f32 v109, v122, v119, v47
	v_pk_mul_f32 v[34:35], v[108:109], v[34:35]
	v_cvt_pk_bf16_f32 v135, v34, v35
	global_store_dwordx4 v4, v[132:135], s[26:27]
	s_mov_b32 s50, 0
	s_add_i32 s12, s12, s90
	s_cmpk_lt_i32 s12, 0x800
	s_cbranch_scc0 .Lmg_nonext
	s_lshl_b32 s16, s12, 3
	s_add_i32 s16, s16, s13
	s_mul_i32 s17, s16, 0x2100
	s_add_u32 s24, s78, s17
	s_addc_u32 s25, s79, 0
	s_add_u32 s26, s24, 0x1900
	s_addc_u32 s27, s25, 0
	s_lshl_b32 s17, s16, 10
	s_add_u32 s28, s80, s17
	s_addc_u32 s29, s81, 0
	s_lshr_b32 s17, s16, 12
	s_lshl_b32 s17, s17, 11
	s_bfe_u32 s19, s16, 0x80004
	s_add_i32 s17, s17, s19
	s_mul_i32 s17, s17, 0x3180
	s_add_u32 s68, s86, s17
	s_addc_u32 s69, s87, 0
	s_and_b32 s19, s16, 15
	s_lshl_b32 s17, s19, 2
	s_addk_i32 s17, 0x3100
	s_add_u32 s30, s68, s17
	s_addc_u32 s31, s69, 0
	s_lshr_b32 s17, s19, 2
	s_lshl_b32 s17, s17, 7
	s_and_b32 s19, s19, 3
	s_lshl_b32 s19, s19, 1
	s_add_i32 s17, s17, s19
	s_addk_i32 s17, 0x2800
	s_add_u32 s32, s68, s17
	s_addc_u32 s33, s69, 0
	global_load_dword v24, v5, s[24:25] offset:3072
	global_load_dword v25, v5, s[24:25] offset:3104
	global_load_dword v26, v5, s[24:25] offset:3136
	global_load_dwordx4 v[28:31], v4, s[24:25] nt
	global_load_dwordx4 v[32:35], v4, s[24:25] offset:1024 nt
	global_load_dwordx4 v[36:39], v4, s[24:25] offset:2048 nt
	global_load_dwordx4 v[44:47], v4, s[26:27] offset:1024 nt
	global_load_dwordx4 v[48:51], v4, s[28:29] nt
	global_load_dwordx4 v[52:55], v4, s[26:27] nt
	global_load_dword v27, v6, s[30:31]
	global_load_ushort v56, v7, s[32:33] offset:0
	global_load_ushort v57, v7, s[32:33] offset:8
	global_load_ushort v58, v7, s[32:33] offset:16
	global_load_ushort v59, v7, s[32:33] offset:24
	global_load_ushort v60, v7, s[32:33] offset:32
	global_load_ushort v61, v7, s[32:33] offset:40
	global_load_ushort v62, v7, s[32:33] offset:48
	global_load_ushort v63, v7, s[32:33] offset:56
	s_waitcnt vmcnt(20)
	s_branch .Lmg_cb
.Lmg_nonext:
	s_waitcnt vmcnt(2)
.Lmg_cb:
	v_max3_f32 v127, v64, v65, v66
	v_sub_f32_e32 v102, v64, v127
	v_sub_f32_e32 v104, v65, v127
	v_sub_f32_e32 v106, v66, v127
	v_mul_f32_e32 v102, 0x3fb8aa3b, v102
	v_mul_f32_e32 v104, 0x3fb8aa3b, v104
	v_mul_f32_e32 v106, 0x3fb8aa3b, v106
	v_exp_f32_e32 v102, v102
	v_exp_f32_e32 v104, v104
	v_exp_f32_e32 v106, v106
	s_nop 0
	v_add_f32_e32 v127, v102, v104
	v_add_f32_e32 v127, v106, v127
	v_div_scale_f32 v122, s[36:37], v127, v127, 1.0
	v_rcp_f32_e32 v123, v122
	v_div_scale_f32 v124, vcc, 1.0, v127, 1.0
	v_fma_f32 v126, -v122, v123, 1.0
	v_fmac_f32_e32 v123, v126, v123
	v_mul_f32_e32 v125, v124, v123
	v_fma_f32 v126, -v122, v125, v124
	v_fmac_f32_e32 v125, v126, v123
	v_fma_f32 v122, -v122, v125, v124
	v_div_fmas_f32 v122, v122, v123, v125
	v_div_fixup_f32 v103, v122, v127, 1.0
	v_mul_f32_e32 v102, v102, v103
	v_mul_f32_e32 v104, v104, v103
	v_mul_f32_e32 v106, v106, v103
	v_lshlrev_b32_e32 v108, 16, v68
	v_and_b32_e32 v109, 0xffff0000, v68
	v_lshlrev_b32_e32 v110, 16, v72
	v_and_b32_e32 v111, 0xffff0000, v72
	v_lshlrev_b32_e32 v112, 16, v76
	v_and_b32_e32 v113, 0xffff0000, v76
	v_lshlrev_b32_e32 v114, 16, v80
	v_and_b32_e32 v115, 0xffff0000, v80
	v_pk_mul_f32 v[116:117], v[108:109], v[102:103] op_sel_hi:[1,0]
	v_pk_fma_f32 v[116:117], v[110:111], v[104:105], v[116:117] op_sel_hi:[1,0,1]
	v_pk_fma_f32 v[116:117], v[112:113], v[106:107], v[116:117] op_sel_hi:[1,0,1]
	v_pk_mul_f32 v[118:119], v[114:115], s[44:45]
	v_exp_f32_e32 v118, v118
	v_exp_f32_e32 v119, v119
	s_nop 0
	v_pk_add_f32 v[118:119], v[118:119], 1.0 op_sel_hi:[1,0]
	v_div_scale_f32 v122, s[36:37], v118, v118, v114
	v_rcp_f32_e32 v123, v122
	v_div_scale_f32 v124, vcc, v114, v118, v114
	v_fma_f32 v126, -v122, v123, 1.0
	v_fmac_f32_e32 v123, v126, v123
	v_mul_f32_e32 v125, v124, v123
	v_fma_f32 v126, -v122, v125, v124
	v_fmac_f32_e32 v125, v126, v123
	v_fma_f32 v122, -v122, v125, v124
	v_div_fmas_f32 v122, v122, v123, v125
	v_div_fixup_f32 v120, v122, v118, v114
	v_div_scale_f32 v122, s[36:37], v119, v119, v115
	v_rcp_f32_e32 v123, v122
	v_div_scale_f32 v124, vcc, v115, v119, v115
	v_fma_f32 v126, -v122, v123, 1.0
	v_fmac_f32_e32 v123, v126, v123
	v_mul_f32_e32 v125, v124, v123
	v_fma_f32 v126, -v122, v125, v124
	v_fmac_f32_e32 v125, v126, v123
	v_fma_f32 v122, -v122, v125, v124
	v_div_fmas_f32 v122, v122, v123, v125
	v_div_fixup_f32 v121, v122, v119, v115
	v_pk_mul_f32 v[116:117], v[120:121], v[116:117]
	v_cvt_pk_bf16_f32 v128, v116, v117
	v_lshlrev_b32_e32 v108, 16, v69
	v_and_b32_e32 v109, 0xffff0000, v69
	v_lshlrev_b32_e32 v110, 16, v73
	v_and_b32_e32 v111, 0xffff0000, v73
	v_lshlrev_b32_e32 v112, 16, v77
	v_and_b32_e32 v113, 0xffff0000, v77
	v_lshlrev_b32_e32 v114, 16, v81
	v_and_b32_e32 v115, 0xffff0000, v81
	v_pk_mul_f32 v[116:117], v[108:109], v[102:103] op_sel_hi:[1,0]
	v_pk_fma_f32 v[116:117], v[110:111], v[104:105], v[116:117] op_sel_hi:[1,0,1]
	v_pk_fma_f32 v[116:117], v[112:113], v[106:107], v[116:117] op_sel_hi:[1,0,1]
	v_pk_mul_f32 v[118:119], v[114:115], s[44:45]
	v_exp_f32_e32 v118, v118
	v_exp_f32_e32 v119, v119
	s_nop 0
	v_pk_add_f32 v[118:119], v[118:119], 1.0 op_sel_hi:[1,0]
	v_div_scale_f32 v122, s[36:37], v118, v118, v114
	v_rcp_f32_e32 v123, v122
	v_div_scale_f32 v124, vcc, v114, v118, v114
	v_fma_f32 v126, -v122, v123, 1.0
	v_fmac_f32_e32 v123, v126, v123
	v_mul_f32_e32 v125, v124, v123
	v_fma_f32 v126, -v122, v125, v124
	v_fmac_f32_e32 v125, v126, v123
	v_fma_f32 v122, -v122, v125, v124
	v_div_fmas_f32 v122, v122, v123, v125
	v_div_fixup_f32 v120, v122, v118, v114
	v_div_scale_f32 v122, s[36:37], v119, v119, v115
	v_rcp_f32_e32 v123, v122
	v_div_scale_f32 v124, vcc, v115, v119, v115
	v_fma_f32 v126, -v122, v123, 1.0
	v_fmac_f32_e32 v123, v126, v123
	v_mul_f32_e32 v125, v124, v123
	v_fma_f32 v126, -v122, v125, v124
	v_fmac_f32_e32 v125, v126, v123
	v_fma_f32 v122, -v122, v125, v124
	v_div_fmas_f32 v122, v122, v123, v125
	v_div_fixup_f32 v121, v122, v119, v115
	v_pk_mul_f32 v[116:117], v[120:121], v[116:117]
	v_cvt_pk_bf16_f32 v129, v116, v117
	v_lshlrev_b32_e32 v108, 16, v70
	v_and_b32_e32 v109, 0xffff0000, v70
	v_lshlrev_b32_e32 v110, 16, v74
	v_and_b32_e32 v111, 0xffff0000, v74
	v_lshlrev_b32_e32 v112, 16, v78
	v_and_b32_e32 v113, 0xffff0000, v78
	v_lshlrev_b32_e32 v114, 16, v82
	v_and_b32_e32 v115, 0xffff0000, v82
	v_pk_mul_f32 v[116:117], v[108:109], v[102:103] op_sel_hi:[1,0]
	v_pk_fma_f32 v[116:117], v[110:111], v[104:105], v[116:117] op_sel_hi:[1,0,1]
	v_pk_fma_f32 v[116:117], v[112:113], v[106:107], v[116:117] op_sel_hi:[1,0,1]
	v_pk_mul_f32 v[118:119], v[114:115], s[44:45]
	v_exp_f32_e32 v118, v118
	v_exp_f32_e32 v119, v119
	s_nop 0
	v_pk_add_f32 v[118:119], v[118:119], 1.0 op_sel_hi:[1,0]
	v_div_scale_f32 v122, s[36:37], v118, v118, v114
	v_rcp_f32_e32 v123, v122
	v_div_scale_f32 v124, vcc, v114, v118, v114
	v_fma_f32 v126, -v122, v123, 1.0
	v_fmac_f32_e32 v123, v126, v123
	v_mul_f32_e32 v125, v124, v123
	v_fma_f32 v126, -v122, v125, v124
	v_fmac_f32_e32 v125, v126, v123
	v_fma_f32 v122, -v122, v125, v124
	v_div_fmas_f32 v122, v122, v123, v125
	v_div_fixup_f32 v120, v122, v118, v114
	v_div_scale_f32 v122, s[36:37], v119, v119, v115
	v_rcp_f32_e32 v123, v122
	v_div_scale_f32 v124, vcc, v115, v119, v115
	v_fma_f32 v126, -v122, v123, 1.0
	v_fmac_f32_e32 v123, v126, v123
	v_mul_f32_e32 v125, v124, v123
	v_fma_f32 v126, -v122, v125, v124
	v_fmac_f32_e32 v125, v126, v123
	v_fma_f32 v122, -v122, v125, v124
	v_div_fmas_f32 v122, v122, v123, v125
	v_div_fixup_f32 v121, v122, v119, v115
	v_pk_mul_f32 v[116:117], v[120:121], v[116:117]
	v_cvt_pk_bf16_f32 v130, v116, v117
	v_lshlrev_b32_e32 v108, 16, v71
	v_and_b32_e32 v109, 0xffff0000, v71
	v_lshlrev_b32_e32 v110, 16, v75
	v_and_b32_e32 v111, 0xffff0000, v75
	v_lshlrev_b32_e32 v112, 16, v79
	v_and_b32_e32 v113, 0xffff0000, v79
	v_lshlrev_b32_e32 v114, 16, v83
	v_and_b32_e32 v115, 0xffff0000, v83
	v_pk_mul_f32 v[116:117], v[108:109], v[102:103] op_sel_hi:[1,0]
	v_pk_fma_f32 v[116:117], v[110:111], v[104:105], v[116:117] op_sel_hi:[1,0,1]
	v_pk_fma_f32 v[116:117], v[112:113], v[106:107], v[116:117] op_sel_hi:[1,0,1]
	v_pk_mul_f32 v[118:119], v[114:115], s[44:45]
	v_exp_f32_e32 v118, v118
	v_exp_f32_e32 v119, v119
	s_nop 0
	v_pk_add_f32 v[118:119], v[118:119], 1.0 op_sel_hi:[1,0]
	v_div_scale_f32 v122, s[36:37], v118, v118, v114
	v_rcp_f32_e32 v123, v122
	v_div_scale_f32 v124, vcc, v114, v118, v114
	v_fma_f32 v126, -v122, v123, 1.0
	v_fmac_f32_e32 v123, v126, v123
	v_mul_f32_e32 v125, v124, v123
	v_fma_f32 v126, -v122, v125, v124
	v_fmac_f32_e32 v125, v126, v123
	v_fma_f32 v122, -v122, v125, v124
	v_div_fmas_f32 v122, v122, v123, v125
	v_div_fixup_f32 v120, v122, v118, v114
	v_div_scale_f32 v122, s[36:37], v119, v119, v115
	v_rcp_f32_e32 v123, v122
	v_div_scale_f32 v124, vcc, v115, v119, v115
	v_fma_f32 v126, -v122, v123, 1.0
	v_fmac_f32_e32 v123, v126, v123
	v_mul_f32_e32 v125, v124, v123
	v_fma_f32 v126, -v122, v125, v124
	v_fmac_f32_e32 v125, v126, v123
	v_fma_f32 v122, -v122, v125, v124
	v_div_fmas_f32 v122, v122, v123, v125
	v_div_fixup_f32 v121, v122, v119, v115
	v_pk_mul_f32 v[116:117], v[120:121], v[116:117]
	v_cvt_pk_bf16_f32 v131, v116, v117
	global_store_dwordx4 v4, v[128:131], s[60:61] offset:1024
	v_lshlrev_b32_e32 v68, 16, v84
	v_and_b32_e32 v69, 0xffff0000, v84
	v_lshlrev_b32_e32 v70, 16, v85
	v_and_b32_e32 v71, 0xffff0000, v85
	v_lshlrev_b32_e32 v72, 16, v86
	v_and_b32_e32 v73, 0xffff0000, v86
	v_lshlrev_b32_e32 v74, 16, v87
	v_and_b32_e32 v75, 0xffff0000, v87
	v_lshlrev_b32_e32 v76, 16, v88
	v_and_b32_e32 v77, 0xffff0000, v88
	v_lshlrev_b32_e32 v78, 16, v89
	v_and_b32_e32 v79, 0xffff0000, v89
	v_lshlrev_b32_e32 v80, 16, v90
	v_and_b32_e32 v81, 0xffff0000, v90
	v_lshlrev_b32_e32 v82, 16, v91
	v_and_b32_e32 v83, 0xffff0000, v91
	v_lshlrev_b32_e32 v92, 16, v92
	v_lshlrev_b32_e32 v93, 16, v93
	v_lshlrev_b32_e32 v94, 16, v94
	v_lshlrev_b32_e32 v95, 16, v95
	v_lshlrev_b32_e32 v96, 16, v96
	v_lshlrev_b32_e32 v97, 16, v97
	v_lshlrev_b32_e32 v98, 16, v98
	v_lshlrev_b32_e32 v99, 16, v99
	v_add_f32_e32 v108, v68, v69
	v_add_f32_e32 v108, v108, v70
	v_add_f32_e32 v108, v108, v71
	v_add_f32_e32 v108, v108, v72
	v_add_f32_e32 v108, v108, v73
	v_add_f32_e32 v108, v108, v74
	v_add_f32_e32 v108, v108, v75
	s_nop 1
	v_add_f32_dpp v109, v108, v108 quad_perm:[1,0,3,2] row_mask:0xf bank_mask:0xf
	s_nop 1
	v_add_f32_dpp v108, v109, v109 quad_perm:[2,3,0,1] row_mask:0xf bank_mask:0xf
	s_nop 1
	v_add_f32_dpp v109, v108, v108 row_half_mirror row_mask:0xf bank_mask:0xf
	v_mov_b32_e32 v108, v109
	v_mul_f32_e32 v108, 0x3c800000, v108
	v_pk_add_f32 v[68:69], v[68:69], v[108:109] op_sel_hi:[1,0] neg_lo:[0,1] neg_hi:[0,1]
	v_pk_add_f32 v[70:71], v[70:71], v[108:109] op_sel_hi:[1,0] neg_lo:[0,1] neg_hi:[0,1]
	v_pk_add_f32 v[72:73], v[72:73], v[108:109] op_sel_hi:[1,0] neg_lo:[0,1] neg_hi:[0,1]
	v_pk_add_f32 v[74:75], v[74:75], v[108:109] op_sel_hi:[1,0] neg_lo:[0,1] neg_hi:[0,1]
	v_pk_mul_f32 v[110:111], v[68:69], v[68:69]
	v_pk_mul_f32 v[112:113], v[70:71], v[70:71]
	v_pk_mul_f32 v[114:115], v[72:73], v[72:73]
	v_pk_mul_f32 v[116:117], v[74:75], v[74:75]
	v_add_f32_e32 v118, v110, v111
	v_add_f32_e32 v118, v112, v118
	v_add_f32_e32 v118, v113, v118
	v_add_f32_e32 v118, v114, v118
	v_add_f32_e32 v118, v115, v118
	v_add_f32_e32 v118, v116, v118
	v_add_f32_e32 v118, v117, v118
	s_nop 1
	v_add_f32_dpp v119, v118, v118 quad_perm:[1,0,3,2] row_mask:0xf bank_mask:0xf
	s_nop 1
	v_add_f32_dpp v118, v119, v119 quad_perm:[2,3,0,1] row_mask:0xf bank_mask:0xf
	s_nop 1
	v_add_f32_dpp v119, v118, v118 row_half_mirror row_mask:0xf bank_mask:0xf
	v_mov_b32_e32 v118, v119
	v_fmamk_f32 v118, v118, 0x3c800000, v100
	v_rsq_f32_e32 v118, v118
	v_mov_b32_e32 v120, v67
	v_pk_mul_f32 v[68:69], v[68:69], v[118:119] op_sel_hi:[1,0]
	v_pk_mul_f32 v[70:71], v[70:71], v[118:119] op_sel_hi:[1,0]
	v_pk_mul_f32 v[72:73], v[72:73], v[118:119] op_sel_hi:[1,0]
	v_pk_mul_f32 v[74:75], v[74:75], v[118:119] op_sel_hi:[1,0]
	v_pk_fma_f32 v[68:69], v[8:9], v[68:69], v[16:17]
	v_pk_fma_f32 v[70:71], v[10:11], v[70:71], v[18:19]
	v_pk_fma_f32 v[72:73], v[12:13], v[72:73], v[20:21]
	v_pk_fma_f32 v[74:75], v[14:15], v[74:75], v[22:23]
	v_pk_fma_f32 v[68:69], v[120:121], v[92:93], v[68:69] op_sel_hi:[0,1,1]
	v_pk_fma_f32 v[70:71], v[120:121], v[94:95], v[70:71] op_sel_hi:[0,1,1]
	v_pk_fma_f32 v[72:73], v[120:121], v[96:97], v[72:73] op_sel_hi:[0,1,1]
	v_pk_fma_f32 v[74:75], v[120:121], v[98:99], v[74:75] op_sel_hi:[0,1,1]
	v_pk_mul_f32 v[118:119], v[76:77], s[44:45]
	v_exp_f32_e32 v118, v118
	v_exp_f32_e32 v119, v119
	s_nop 0
	v_pk_add_f32 v[118:119], v[118:119], 1.0 op_sel_hi:[1,0]
	v_div_scale_f32 v122, s[36:37], v118, v118, v76
	v_rcp_f32_e32 v123, v122
	v_div_scale_f32 v124, vcc, v76, v118, v76
	v_fma_f32 v126, -v122, v123, 1.0
	v_fmac_f32_e32 v123, v126, v123
	v_mul_f32_e32 v125, v124, v123
	v_fma_f32 v126, -v122, v125, v124
	v_fmac_f32_e32 v125, v126, v123
	v_fma_f32 v122, -v122, v125, v124
	v_div_fmas_f32 v122, v122, v123, v125
	v_div_fixup_f32 v108, v122, v118, v76
	v_div_scale_f32 v122, s[36:37], v119, v119, v77
	v_rcp_f32_e32 v123, v122
	v_div_scale_f32 v124, vcc, v77, v119, v77
	v_fma_f32 v126, -v122, v123, 1.0
	v_fmac_f32_e32 v123, v126, v123
	v_mul_f32_e32 v125, v124, v123
	v_fma_f32 v126, -v122, v125, v124
	v_fmac_f32_e32 v125, v126, v123
	v_fma_f32 v122, -v122, v125, v124
	v_div_fmas_f32 v122, v122, v123, v125
	v_div_fixup_f32 v109, v122, v119, v77
	v_pk_mul_f32 v[68:69], v[108:109], v[68:69]
	v_cvt_pk_bf16_f32 v132, v68, v69
	v_pk_mul_f32 v[118:119], v[78:79], s[44:45]
	v_exp_f32_e32 v118, v118
	v_exp_f32_e32 v119, v119
	s_nop 0
	v_pk_add_f32 v[118:119], v[118:119], 1.0 op_sel_hi:[1,0]
	v_div_scale_f32 v122, s[36:37], v118, v118, v78
	v_rcp_f32_e32 v123, v122
	v_div_scale_f32 v124, vcc, v78, v118, v78
	v_fma_f32 v126, -v122, v123, 1.0
	v_fmac_f32_e32 v123, v126, v123
	v_mul_f32_e32 v125, v124, v123
	v_fma_f32 v126, -v122, v125, v124
	v_fmac_f32_e32 v125, v126, v123
	v_fma_f32 v122, -v122, v125, v124
	v_div_fmas_f32 v122, v122, v123, v125
	v_div_fixup_f32 v108, v122, v118, v78
	v_div_scale_f32 v122, s[36:37], v119, v119, v79
	v_rcp_f32_e32 v123, v122
	v_div_scale_f32 v124, vcc, v79, v119, v79
	v_fma_f32 v126, -v122, v123, 1.0
	v_fmac_f32_e32 v123, v126, v123
	v_mul_f32_e32 v125, v124, v123
	v_fma_f32 v126, -v122, v125, v124
	v_fmac_f32_e32 v125, v126, v123
	v_fma_f32 v122, -v122, v125, v124
	v_div_fmas_f32 v122, v122, v123, v125
	v_div_fixup_f32 v109, v122, v119, v79
	v_pk_mul_f32 v[70:71], v[108:109], v[70:71]
	v_cvt_pk_bf16_f32 v133, v70, v71
	v_pk_mul_f32 v[118:119], v[80:81], s[44:45]
	v_exp_f32_e32 v118, v118
	v_exp_f32_e32 v119, v119
	s_nop 0
	v_pk_add_f32 v[118:119], v[118:119], 1.0 op_sel_hi:[1,0]
	v_div_scale_f32 v122, s[36:37], v118, v118, v80
	v_rcp_f32_e32 v123, v122
	v_div_scale_f32 v124, vcc, v80, v118, v80
	v_fma_f32 v126, -v122, v123, 1.0
	v_fmac_f32_e32 v123, v126, v123
	v_mul_f32_e32 v125, v124, v123
	v_fma_f32 v126, -v122, v125, v124
	v_fmac_f32_e32 v125, v126, v123
	v_fma_f32 v122, -v122, v125, v124
	v_div_fmas_f32 v122, v122, v123, v125
	v_div_fixup_f32 v108, v122, v118, v80
	v_div_scale_f32 v122, s[36:37], v119, v119, v81
	v_rcp_f32_e32 v123, v122
	v_div_scale_f32 v124, vcc, v81, v119, v81
	v_fma_f32 v126, -v122, v123, 1.0
	v_fmac_f32_e32 v123, v126, v123
	v_mul_f32_e32 v125, v124, v123
	v_fma_f32 v126, -v122, v125, v124
	v_fmac_f32_e32 v125, v126, v123
	v_fma_f32 v122, -v122, v125, v124
	v_div_fmas_f32 v122, v122, v123, v125
	v_div_fixup_f32 v109, v122, v119, v81
	v_pk_mul_f32 v[72:73], v[108:109], v[72:73]
	v_cvt_pk_bf16_f32 v134, v72, v73
	v_pk_mul_f32 v[118:119], v[82:83], s[44:45]
	v_exp_f32_e32 v118, v118
	v_exp_f32_e32 v119, v119
	s_nop 0
	v_pk_add_f32 v[118:119], v[118:119], 1.0 op_sel_hi:[1,0]
	v_div_scale_f32 v122, s[36:37], v118, v118, v82
	v_rcp_f32_e32 v123, v122
	v_div_scale_f32 v124, vcc, v82, v118, v82
	v_fma_f32 v126, -v122, v123, 1.0
	v_fmac_f32_e32 v123, v126, v123
	v_mul_f32_e32 v125, v124, v123
	v_fma_f32 v126, -v122, v125, v124
	v_fmac_f32_e32 v125, v126, v123
	v_fma_f32 v122, -v122, v125, v124
	v_div_fmas_f32 v122, v122, v123, v125
	v_div_fixup_f32 v108, v122, v118, v82
	v_div_scale_f32 v122, s[36:37], v119, v119, v83
	v_rcp_f32_e32 v123, v122
	v_div_scale_f32 v124, vcc, v83, v119, v83
	v_fma_f32 v126, -v122, v123, 1.0
	v_fmac_f32_e32 v123, v126, v123
	v_mul_f32_e32 v125, v124, v123
	v_fma_f32 v126, -v122, v125, v124
	v_fmac_f32_e32 v125, v126, v123
	v_fma_f32 v122, -v122, v125, v124
	v_div_fmas_f32 v122, v122, v123, v125
	v_div_fixup_f32 v109, v122, v119, v83
	v_pk_mul_f32 v[74:75], v[108:109], v[74:75]
	v_cvt_pk_bf16_f32 v135, v74, v75
	global_store_dwordx4 v4, v[132:135], s[60:61]
	s_cmpk_lt_i32 s12, 0x800
	s_cbranch_scc1 .Lmg_loop
